# GDN staging waves: hand-written staging loop for prompt blocks 1..126 (5 loads, convert, 11 LDS writes, pointer bumps) replacing the per-block descriptor and address code
# baseline (speedup 1.0000x reference)
.LBB0_939:
	s_and_b64 vcc, exec, s[38:39]
	s_cbranch_vccnz .Lgh_no
	s_cmp_eq_u32 s2, 1
	s_cbranch_scc0 .Lgh_no
	v_and_b32_e32 v32, 0x7f, v142
	v_readlane_b32 s4, v254, 0
	v_readlane_b32 s5, v254, 1
	s_nop 1
	s_add_u32 s4, s4, 32
	s_addc_u32 s5, s5, 0
	s_lshl_b64 s[100:101], s[4:5], 10
	v_readlane_b32 s4, v254, 2
	v_readlane_b32 s5, v254, 3
	s_nop 1
	s_add_u32 s4, s4, s100
	s_addc_u32 s5, s5, s101
	v_readlane_b32 s100, v254, 6
	s_nop 1
	s_lshl_b32 s100, s100, 8
	v_bfe_u32 v33, v32, 4, 1
	v_lshlrev_b32_e32 v46, 24, v33
	v_lshl_add_u32 v33, v33, 20, v46
	v_lshrrev_b32_e32 v40, 5, v32
	v_lshl_add_u32 v33, v40, 10, v33
	v_and_b32_e32 v41, 15, v32
	v_lshl_add_u32 v33, v41, 4, v33
	v_add_u32_e32 v33, s100, v33
	v_add_u32_e32 v34, 0x800, v33
	v_mov_b32_e32 v35, 0
	v_lshl_add_u64 v[34:35], s[4:5], 0, v[34:35]
	s_mov_b64 vcc, 0x2000
	v_lshl_add_u64 v[36:37], v[34:35], 0, vcc
	v_lshlrev_b32_e32 v42, 10, v40
	v_bfe_u32 v33, v32, 4, 1
	v_lshl_add_u32 v42, v33, 9, v42
	v_and_b32_e32 v33, 1, v41
	v_lshl_add_u32 v42, v33, 8, v42
	v_lshrrev_b32_e32 v33, 1, v41
	v_lshl_add_u32 v42, v33, 4, v42
	s_cmp_eq_u32 s58, 1
	s_cbranch_scc1 .Lgh_top
	v_readlane_b32 s4, v254, 0
	v_readlane_b32 s5, v254, 1
	s_nop 1
	s_add_u32 s4, s4, 32
	s_addc_u32 s5, s5, 0
	v_lshrrev_b32_e32 v33, 1, v32
	v_mov_b32_e32 v45, 0
	v_mov_b32_e32 v44, v33
	v_lshl_add_u64 v[44:45], s[4:5], 0, v[44:45]
	v_lshlrev_b64 v[44:45], 10, v[44:45]
	v_readlane_b32 s4, v254, 11
	v_readlane_b32 s5, v254, 12
	s_nop 1
	v_lshl_add_u64 v[44:45], v[44:45], 0, s[4:5]
	s_and_b32 s4, s33, 7
	s_lshl_b32 s4, s4, 5
	s_add_i32 s4, s4, s100
	v_and_b32_e32 v46, 1, v32
	v_lshl_add_u32 v46, v46, 4, s4
	v_mov_b32_e32 v47, 0
	v_lshl_add_u64 v[44:45], v[44:45], 0, v[46:47]
	v_readlane_b32 s4, v254, 0
	v_readlane_b32 s5, v254, 1
	s_nop 1
	s_add_u32 s4, s4, 32
	s_addc_u32 s5, s5, 0
	v_subrev_u32_e32 v48, 32, v32
	v_and_b32_e32 v48, 15, v48
	v_mov_b32_e32 v49, 0
	v_lshl_add_u64 v[50:51], s[4:5], 0, v[48:49]
	v_lshlrev_b64 v[50:51], 6, v[50:51]
	v_readlane_b32 s4, v254, 7
	v_readlane_b32 s5, v254, 8
	s_nop 1
	v_lshl_add_u64 v[50:51], v[50:51], 0, s[4:5]
	s_lshr_b32 s4, s100, 4
	s_mov_b32 s5, 0
	v_lshl_add_u64 v[50:51], v[50:51], 0, s[4:5]
	v_cmp_gt_u32_e32 vcc, 32, v32
	s_nop 1
	v_cndmask_b32_e32 v38, v50, v44, vcc
	v_cndmask_b32_e32 v39, v51, v45, vcc
	v_mov_b32_e32 v40, 0x400
	v_mov_b32_e32 v33, 0x4000
	v_cndmask_b32_e32 v40, v40, v33, vcc
	v_mov_b32_e32 v41, 0
	v_lshrrev_b32_e32 v33, 1, v32
	v_lshlrev_b32_e32 v33, 6, v33
	v_and_b32_e32 v46, 1, v32
	v_lshl_add_u32 v33, v46, 5, v33
	v_add_u32_e32 v33, 0x4000, v33
	v_lshlrev_b32_e32 v46, 4, v48
	v_add_u32_e32 v46, 0x4400, v46
	v_cndmask_b32_e32 v43, v46, v33, vcc
.Lgh_top:
	v_mov_b32_e32 v41, 0
	s_add_i32 s4, s2, 1
	s_and_b32 s4, s4, 1
	s_mul_i32 s4, s4, 0x4500
	s_add_i32 s4, s4, 0xa900
	global_load_dwordx4 v[52:55], v[34:35], off offset:-2048
	global_load_dwordx4 v[56:59], v[34:35], off offset:2048
	global_load_dwordx4 v[60:63], v[36:37], off offset:-2048
	global_load_dwordx4 v[64:67], v[36:37], off offset:2048
	s_cmp_eq_u32 s58, 1
	s_cbranch_scc1 .Lgh_l5
	s_mov_b32 exec_hi, 0xffff
	global_load_dwordx4 v[68:71], v[38:39], off
	v_lshl_add_u64 v[38:39], v[38:39], 0, v[40:41]
	s_mov_b32 exec_hi, -1
.Lgh_l5:
	s_mov_b64 vcc, 0x4000
	v_lshl_add_u64 v[34:35], v[34:35], 0, vcc
	v_lshl_add_u64 v[36:37], v[36:37], 0, vcc
	v_add_u32_e32 v33, s4, v42
	s_waitcnt vmcnt(0)
	v_lshlrev_b32_e32 v72, 16, v52
	v_and_b32_e32 v73, 0xffff0000, v52
	v_lshlrev_b32_e32 v74, 16, v53
	v_and_b32_e32 v75, 0xffff0000, v53
	ds_write_b128 v33, v[72:75]
	v_lshlrev_b32_e32 v72, 16, v54
	v_and_b32_e32 v73, 0xffff0000, v54
	v_lshlrev_b32_e32 v74, 16, v55
	v_and_b32_e32 v75, 0xffff0000, v55
	ds_write_b128 v33, v[72:75] offset:128
	v_lshlrev_b32_e32 v72, 16, v56
	v_and_b32_e32 v73, 0xffff0000, v56
	v_lshlrev_b32_e32 v74, 16, v57
	v_and_b32_e32 v75, 0xffff0000, v57
	ds_write_b128 v33, v[72:75] offset:4096
	v_lshlrev_b32_e32 v72, 16, v58
	v_and_b32_e32 v73, 0xffff0000, v58
	v_lshlrev_b32_e32 v74, 16, v59
	v_and_b32_e32 v75, 0xffff0000, v59
	ds_write_b128 v33, v[72:75] offset:4224
	v_lshlrev_b32_e32 v72, 16, v60
	v_and_b32_e32 v73, 0xffff0000, v60
	v_lshlrev_b32_e32 v74, 16, v61
	v_and_b32_e32 v75, 0xffff0000, v61
	ds_write_b128 v33, v[72:75] offset:8192
	v_lshlrev_b32_e32 v72, 16, v62
	v_and_b32_e32 v73, 0xffff0000, v62
	v_lshlrev_b32_e32 v74, 16, v63
	v_and_b32_e32 v75, 0xffff0000, v63
	ds_write_b128 v33, v[72:75] offset:8320
	v_lshlrev_b32_e32 v72, 16, v64
	v_and_b32_e32 v73, 0xffff0000, v64
	v_lshlrev_b32_e32 v74, 16, v65
	v_and_b32_e32 v75, 0xffff0000, v65
	ds_write_b128 v33, v[72:75] offset:12288
	v_lshlrev_b32_e32 v72, 16, v66
	v_and_b32_e32 v73, 0xffff0000, v66
	v_lshlrev_b32_e32 v74, 16, v67
	v_and_b32_e32 v75, 0xffff0000, v67
	ds_write_b128 v33, v[72:75] offset:12416
	s_cmp_eq_u32 s58, 1
	s_cbranch_scc1 .Lgh_w5
	v_add_u32_e32 v44, s4, v43
	s_mov_b32 exec_hi, 0
	v_lshlrev_b32_e32 v72, 16, v68
	v_and_b32_e32 v73, 0xffff0000, v68
	v_lshlrev_b32_e32 v74, 16, v69
	v_and_b32_e32 v75, 0xffff0000, v69
	ds_write_b128 v44, v[72:75]
	v_lshlrev_b32_e32 v72, 16, v70
	v_and_b32_e32 v73, 0xffff0000, v70
	v_lshlrev_b32_e32 v74, 16, v71
	v_and_b32_e32 v75, 0xffff0000, v71
	ds_write_b128 v44, v[72:75] offset:16
	s_mov_b32 exec_lo, 0
	s_mov_b32 exec_hi, 0xffff
	ds_write_b128 v44, v[68:71]
	s_mov_b64 exec, -1
.Lgh_w5:
	s_add_i32 s2, s2, 1
	s_waitcnt lgkmcnt(0)
	s_barrier
	s_cmpk_lt_u32 s2, 0x7f
	s_cbranch_scc1 .Lgh_top

; __global__ void __launch_bounds__(NTHR, 2) hybrid_fwd(Args args) {
;     extern __shared__ __attribute__((aligned(16))) unsigned char lds_raw[];
	.amdhsa_kernel _Z10hybrid_fwd4Args
		.amdhsa_group_segment_fixed_size 0
		.amdhsa_private_segment_fixed_size 0
		.amdhsa_kernarg_size 592
		.amdhsa_user_sgpr_count 2
		.amdhsa_user_sgpr_dispatch_ptr 0
		.amdhsa_user_sgpr_queue_ptr 0
		.amdhsa_user_sgpr_kernarg_segment_ptr 1
		.amdhsa_user_sgpr_dispatch_id 0
		.amdhsa_user_sgpr_kernarg_preload_length 0
		.amdhsa_user_sgpr_kernarg_preload_offset 0
		.amdhsa_user_sgpr_private_segment_size 0
		.amdhsa_uses_dynamic_stack 0
		.amdhsa_enable_private_segment 0
		.amdhsa_system_sgpr_workgroup_id_x 1
		.amdhsa_system_sgpr_workgroup_id_y 0
		.amdhsa_system_sgpr_workgroup_id_z 0
		.amdhsa_system_sgpr_workgroup_info 0
		.amdhsa_system_vgpr_workitem_id 2
		.amdhsa_next_free_vgpr 256
		.amdhsa_next_free_sgpr 102
		.amdhsa_accum_offset 256
		.amdhsa_reserve_vcc 1
		.amdhsa_float_round_mode_32 0
		.amdhsa_float_round_mode_16_64 0
		.amdhsa_float_denorm_mode_32 3
		.amdhsa_float_denorm_mode_16_64 3
		.amdhsa_dx10_clamp 1
		.amdhsa_ieee_mode 1
		.amdhsa_fp16_overflow 0
		.amdhsa_tg_split 0
		.amdhsa_exception_fp_ieee_invalid_op 0
		.amdhsa_exception_fp_denorm_src 0
		.amdhsa_exception_fp_ieee_div_zero 0
		.amdhsa_exception_fp_ieee_overflow 0
		.amdhsa_exception_fp_ieee_underflow 0
		.amdhsa_exception_fp_ieee_inexact 0
		.amdhsa_exception_int_div_zero 0
	.end_amdhsa_kernel

; __global__ void __launch_bounds__(NTHR, 2) hybrid_fwd(Args args) {
;     extern __shared__ __attribute__((aligned(16))) unsigned char lds_raw[];
amdhsa.kernels:
  - .agpr_count:     0
    .args:
      - .offset:         0
        .size:           336
        .value_kind:     by_value
      - .offset:         336
        .size:           4
        .value_kind:     hidden_block_count_x
      - .offset:         340
        .size:           4
        .value_kind:     hidden_block_count_y
      - .offset:         344
        .size:           4
        .value_kind:     hidden_block_count_z
      - .offset:         348
        .size:           2
        .value_kind:     hidden_group_size_x
      - .offset:         350
        .size:           2
        .value_kind:     hidden_group_size_y
      - .offset:         352
        .size:           2
        .value_kind:     hidden_group_size_z
      - .offset:         354
        .size:           2
        .value_kind:     hidden_remainder_x
      - .offset:         356
        .size:           2
        .value_kind:     hidden_remainder_y
      - .offset:         358
        .size:           2
        .value_kind:     hidden_remainder_z
      - .offset:         376
        .size:           8
        .value_kind:     hidden_global_offset_x
      - .offset:         384
        .size:           8
        .value_kind:     hidden_global_offset_y
      - .offset:         392
        .size:           8
        .value_kind:     hidden_global_offset_z
      - .offset:         400
        .size:           2
        .value_kind:     hidden_grid_dims
      - .offset:         424
        .size:           8
        .value_kind:     hidden_multigrid_sync_arg
      - .offset:         456
        .size:           4
        .value_kind:     hidden_dynamic_lds_size
    .group_segment_fixed_size: 0
    .kernarg_segment_align: 8
    .kernarg_segment_size: 592
    .language:       OpenCL C
    .language_version:
      - 2
      - 0
    .max_flat_workgroup_size: 512
    .name:           _Z10hybrid_fwd4Args
    .private_segment_fixed_size: 0
    .sgpr_count:     108
    .sgpr_spill_count: 402
    .symbol:         _Z10hybrid_fwd4Args.kd
    .uniform_work_group_size: 1
    .uses_dynamic_stack: false
    .vgpr_count:     256
    .vgpr_spill_count: 0
    .wavefront_size: 64
